# P0 streaming loops: 8 loads in flight per thread with counted vmcnt instead of 1 load + vmcnt(0)
# baseline (speedup 1.0000x reference)
;     __device__ __forceinline__ bf16_t* XB() const { return (bf16_t*)(ws + WS_XB); }
; #define CVT_REGION(src, dst, n4) do { const f32x4* s4_ = (const f32x4*)(src); unsigned long long* d8_ = (unsigned long long*)(dst); \
;         _Pragma("unroll 4") for (int i_ = gt; i_ < (n4); i_ += NT) { const f32x4 v_ = __builtin_nontemporal_load(s4_ + i_); d8_[i_] = (unsigned long long)pk2(v_.x, v_.y) | ((unsigned long long)pk2(v_.z, v_.w) << 32); } } while (0)
; __device__ __forceinline__ void p0_prologue(const Args& p, LAS unsigned char* lds, int G, int bid, int tid) {
;     ...
;     CVT_REGION(p.x_prompt(), p.XB(), NPT * (DM / 4));
;     CVT_REGION(p.x_sample(), p.XB() + (size_t)NPT * DM, NST * (DM / 4));
.LBB0_74:
	s_or_b64 exec, exec, s[0:1]
	v_lshlrev_b32_e32 v32, 4, v192
	v_lshlrev_b32_e32 v33, 3, v192
	v_readlane_b32 s4, v242, 19
	v_readlane_b32 s5, v242, 20
	s_nop 3
	s_lshl_b32 s11, s94, 13
	s_add_u32 s4, s4, s11
	s_addc_u32 s5, s5, 0
	s_add_u32 s6, s58, 0x2c00000
	s_addc_u32 s7, s59, 0
	s_lshl_b32 s11, s94, 12
	s_add_u32 s6, s6, s11
	s_addc_u32 s7, s7, 0
	s_lshl_b32 s8, s96, 13
	s_lshl_b32 s9, s96, 12
	s_mov_b32 s10, 0
	s_mov_b32 s11, s94
.Lp0s_cnt_xp:
	s_cmp_ge_u32 s11, 0x2000
	s_cbranch_scc1 .Lp0s_cntd_xp
	s_add_u32 s10, s10, 1
	s_add_u32 s11, s11, s96
	s_branch .Lp0s_cnt_xp
.Lp0s_cntd_xp:
.Lp0s_loop_xp:
	s_cmp_lt_u32 s10, 8
	s_cbranch_scc1 .Lp0s_tail_xp
	global_load_dwordx4 v[36:39], v32, s[4:5] nt
	s_add_u32 s4, s4, s8
	s_addc_u32 s5, s5, 0
	global_load_dwordx4 v[40:43], v32, s[4:5] nt
	s_add_u32 s4, s4, s8
	s_addc_u32 s5, s5, 0
	global_load_dwordx4 v[44:47], v32, s[4:5] nt
	s_add_u32 s4, s4, s8
	s_addc_u32 s5, s5, 0
	global_load_dwordx4 v[48:51], v32, s[4:5] nt
	s_add_u32 s4, s4, s8
	s_addc_u32 s5, s5, 0
	global_load_dwordx4 v[52:55], v32, s[4:5] nt
	s_add_u32 s4, s4, s8
	s_addc_u32 s5, s5, 0
	global_load_dwordx4 v[56:59], v32, s[4:5] nt
	s_add_u32 s4, s4, s8
	s_addc_u32 s5, s5, 0
	global_load_dwordx4 v[60:63], v32, s[4:5] nt
	s_add_u32 s4, s4, s8
	s_addc_u32 s5, s5, 0
	global_load_dwordx4 v[64:67], v32, s[4:5] nt
	s_add_u32 s4, s4, s8
	s_addc_u32 s5, s5, 0
	s_waitcnt vmcnt(7)
	v_cvt_pk_bf16_f32 v36, v36, v37
	v_cvt_pk_bf16_f32 v37, v38, v39
	global_store_dwordx2 v33, v[36:37], s[6:7]
	s_add_u32 s6, s6, s9
	s_addc_u32 s7, s7, 0
	s_waitcnt vmcnt(7)
	v_cvt_pk_bf16_f32 v40, v40, v41
	v_cvt_pk_bf16_f32 v41, v42, v43
	global_store_dwordx2 v33, v[40:41], s[6:7]
	s_add_u32 s6, s6, s9
	s_addc_u32 s7, s7, 0
	s_waitcnt vmcnt(7)
	v_cvt_pk_bf16_f32 v44, v44, v45
	v_cvt_pk_bf16_f32 v45, v46, v47
	global_store_dwordx2 v33, v[44:45], s[6:7]
	s_add_u32 s6, s6, s9
	s_addc_u32 s7, s7, 0
	s_waitcnt vmcnt(7)
	v_cvt_pk_bf16_f32 v48, v48, v49
	v_cvt_pk_bf16_f32 v49, v50, v51
	global_store_dwordx2 v33, v[48:49], s[6:7]
	s_add_u32 s6, s6, s9
	s_addc_u32 s7, s7, 0
	s_waitcnt vmcnt(7)
	v_cvt_pk_bf16_f32 v52, v52, v53
	v_cvt_pk_bf16_f32 v53, v54, v55
	global_store_dwordx2 v33, v[52:53], s[6:7]
	s_add_u32 s6, s6, s9
	s_addc_u32 s7, s7, 0
	s_waitcnt vmcnt(7)
	v_cvt_pk_bf16_f32 v56, v56, v57
	v_cvt_pk_bf16_f32 v57, v58, v59
	global_store_dwordx2 v33, v[56:57], s[6:7]
	s_add_u32 s6, s6, s9
	s_addc_u32 s7, s7, 0
	s_waitcnt vmcnt(7)
	v_cvt_pk_bf16_f32 v60, v60, v61
	v_cvt_pk_bf16_f32 v61, v62, v63
	global_store_dwordx2 v33, v[60:61], s[6:7]
	s_add_u32 s6, s6, s9
	s_addc_u32 s7, s7, 0
	s_waitcnt vmcnt(7)
	v_cvt_pk_bf16_f32 v64, v64, v65
	v_cvt_pk_bf16_f32 v65, v66, v67
	global_store_dwordx2 v33, v[64:65], s[6:7]
	s_add_u32 s6, s6, s9
	s_addc_u32 s7, s7, 0
	s_sub_u32 s10, s10, 8
	s_branch .Lp0s_loop_xp
.Lp0s_tail_xp:
	s_cmp_gt_u32 s10, 0
	s_cbranch_scc0 .Lp0s_tl_xp
	global_load_dwordx4 v[36:39], v32, s[4:5] nt
	s_add_u32 s4, s4, s8
	s_addc_u32 s5, s5, 0
	s_cmp_gt_u32 s10, 1
	s_cbranch_scc0 .Lp0s_tl_xp
	global_load_dwordx4 v[40:43], v32, s[4:5] nt
	s_add_u32 s4, s4, s8
	s_addc_u32 s5, s5, 0
	s_cmp_gt_u32 s10, 2
	s_cbranch_scc0 .Lp0s_tl_xp
	global_load_dwordx4 v[44:47], v32, s[4:5] nt
	s_add_u32 s4, s4, s8
	s_addc_u32 s5, s5, 0
	s_cmp_gt_u32 s10, 3
	s_cbranch_scc0 .Lp0s_tl_xp
	global_load_dwordx4 v[48:51], v32, s[4:5] nt
	s_add_u32 s4, s4, s8
	s_addc_u32 s5, s5, 0
	s_cmp_gt_u32 s10, 4
	s_cbranch_scc0 .Lp0s_tl_xp
	global_load_dwordx4 v[52:55], v32, s[4:5] nt
	s_add_u32 s4, s4, s8
	s_addc_u32 s5, s5, 0
	s_cmp_gt_u32 s10, 5
	s_cbranch_scc0 .Lp0s_tl_xp
	global_load_dwordx4 v[56:59], v32, s[4:5] nt
	s_add_u32 s4, s4, s8
	s_addc_u32 s5, s5, 0
	s_cmp_gt_u32 s10, 6
	s_cbranch_scc0 .Lp0s_tl_xp
	global_load_dwordx4 v[60:63], v32, s[4:5] nt
	s_add_u32 s4, s4, s8
	s_addc_u32 s5, s5, 0
.Lp0s_tl_xp:
	s_waitcnt vmcnt(0)
	s_cmp_gt_u32 s10, 0
	s_cbranch_scc0 .Lp0s_ts_xp
	v_cvt_pk_bf16_f32 v36, v36, v37
	v_cvt_pk_bf16_f32 v37, v38, v39
	global_store_dwordx2 v33, v[36:37], s[6:7]
	s_add_u32 s6, s6, s9
	s_addc_u32 s7, s7, 0
	s_cmp_gt_u32 s10, 1
	s_cbranch_scc0 .Lp0s_ts_xp
	v_cvt_pk_bf16_f32 v40, v40, v41
	v_cvt_pk_bf16_f32 v41, v42, v43
	global_store_dwordx2 v33, v[40:41], s[6:7]
	s_add_u32 s6, s6, s9
	s_addc_u32 s7, s7, 0
	s_cmp_gt_u32 s10, 2
	s_cbranch_scc0 .Lp0s_ts_xp
	v_cvt_pk_bf16_f32 v44, v44, v45
	v_cvt_pk_bf16_f32 v45, v46, v47
	global_store_dwordx2 v33, v[44:45], s[6:7]
	s_add_u32 s6, s6, s9
	s_addc_u32 s7, s7, 0
	s_cmp_gt_u32 s10, 3
	s_cbranch_scc0 .Lp0s_ts_xp
	v_cvt_pk_bf16_f32 v48, v48, v49
	v_cvt_pk_bf16_f32 v49, v50, v51
	global_store_dwordx2 v33, v[48:49], s[6:7]
	s_add_u32 s6, s6, s9
	s_addc_u32 s7, s7, 0
	s_cmp_gt_u32 s10, 4
	s_cbranch_scc0 .Lp0s_ts_xp
	v_cvt_pk_bf16_f32 v52, v52, v53
	v_cvt_pk_bf16_f32 v53, v54, v55
	global_store_dwordx2 v33, v[52:53], s[6:7]
	s_add_u32 s6, s6, s9
	s_addc_u32 s7, s7, 0
	s_cmp_gt_u32 s10, 5
	s_cbranch_scc0 .Lp0s_ts_xp
	v_cvt_pk_bf16_f32 v56, v56, v57
	v_cvt_pk_bf16_f32 v57, v58, v59
	global_store_dwordx2 v33, v[56:57], s[6:7]
	s_add_u32 s6, s6, s9
	s_addc_u32 s7, s7, 0
	s_cmp_gt_u32 s10, 6
	s_cbranch_scc0 .Lp0s_ts_xp
	v_cvt_pk_bf16_f32 v60, v60, v61
	v_cvt_pk_bf16_f32 v61, v62, v63
	global_store_dwordx2 v33, v[60:61], s[6:7]
	s_add_u32 s6, s6, s9
	s_addc_u32 s7, s7, 0
.Lp0s_ts_xp:
	v_readlane_b32 s4, v242, 21
	v_readlane_b32 s5, v242, 22
	s_nop 3
	s_lshl_b32 s11, s94, 13
	s_add_u32 s4, s4, s11
	s_addc_u32 s5, s5, 0
	s_add_u32 s6, s58, 0x4c00000
	s_addc_u32 s7, s59, 0
	s_lshl_b32 s11, s94, 12
	s_add_u32 s6, s6, s11
	s_addc_u32 s7, s7, 0
	s_lshl_b32 s8, s96, 13
	s_lshl_b32 s9, s96, 12
	s_mov_b32 s10, 0
	s_mov_b32 s11, s94
.Lp0s_cnt_xs:
	s_cmp_ge_u32 s11, 0x100
	s_cbranch_scc1 .Lp0s_cntd_xs
	s_add_u32 s10, s10, 1
	s_add_u32 s11, s11, s96
	s_branch .Lp0s_cnt_xs

;     __device__ __forceinline__ bf16_t* MB() const { return (bf16_t*)(ws + WS_MB); }
; #define CVT_REGION(src, dst, n4) do { const f32x4* s4_ = (const f32x4*)(src); unsigned long long* d8_ = (unsigned long long*)(dst); \
;         _Pragma("unroll 4") for (int i_ = gt; i_ < (n4); i_ += NT) { const f32x4 v_ = __builtin_nontemporal_load(s4_ + i_); d8_[i_] = (unsigned long long)pk2(v_.x, v_.y) | ((unsigned long long)pk2(v_.z, v_.w) << 32); } } while (0)
; __device__ __forceinline__ void p0_prologue(const Args& p, LAS unsigned char* lds, int G, int bid, int tid) {
;     ...
;     CVT_REGION(p.mem_prompt(), p.MB(), MEMROWS * (DM / 4));
.Lp0s_ts_xs:
	v_readlane_b32 s4, v242, 23
	v_readlane_b32 s5, v242, 24
	s_nop 3
	s_lshl_b32 s11, s94, 13
	s_add_u32 s4, s4, s11
	s_addc_u32 s5, s5, 0
	s_add_u32 s6, s58, 0x2700000
	s_addc_u32 s7, s59, 0
	s_lshl_b32 s11, s94, 12
	s_add_u32 s6, s6, s11
	s_addc_u32 s7, s7, 0
	s_lshl_b32 s8, s96, 13
	s_lshl_b32 s9, s96, 12
	s_mov_b32 s10, 0
	s_mov_b32 s11, s94
.Lp0s_cnt_mb:
	s_cmp_ge_u32 s11, 0x400
	s_cbranch_scc1 .Lp0s_cntd_mb
	s_add_u32 s10, s10, 1
	s_add_u32 s11, s11, s96
	s_branch .Lp0s_cnt_mb

; __device__ __forceinline__ void p0_prologue(const Args& p, LAS unsigned char* lds, int G, int bid, int tid) {
;     ...
;     for (int i = gt; i < DECB * 3328; i += NT) { const int sb = i / 3328, o = i % 3328; __builtin_nontemporal_store(__builtin_nontemporal_load((const f32x4*)(p.state_conv() + (size_t)sb * 15360 + 2048) + o), (f32x4*)(p.out() + OCS + (size_t)sb * 15360) + o); }
.Lp0s_ts_mb:
	v_readlane_b32 s4, v242, 29
	v_readlane_b32 s5, v242, 30
	s_nop 3
	s_add_u32 s4, s4, 0x2000
	s_addc_u32 s5, s5, 0
	s_add_u32 s6, s56, 0x5278000
	s_addc_u32 s7, s57, 0
	s_lshl_b32 s12, s94, 9
	s_lshl_b32 s8, s96, 9
	s_mov_b32 s13, 0x4ec4ec4f
	s_mov_b32 s10, 0
	s_mov_b32 s11, s94
.Lp0s_cnt_sc:
	s_cmp_ge_u32 s11, 0x340
	s_cbranch_scc1 .Lp0s_cntd_sc
	s_add_u32 s10, s10, 1
	s_add_u32 s11, s11, s96
	s_branch .Lp0s_cnt_sc
.Lp0s_cntd_sc:
.Lp0s_loop_sc:
	s_cmp_lt_u32 s10, 8
	s_cbranch_scc1 .Lp0s_tail_sc
	v_add_u32_e32 v34, s12, v192
	v_mul_hi_u32 v35, v34, s13
	v_lshrrev_b32_e32 v35, 10, v35
	v_lshlrev_b32_e32 v34, 4, v34
	v_lshl_add_u32 v68, v35, 13, v34
	s_add_u32 s12, s12, s8
	global_load_dwordx4 v[36:39], v68, s[4:5] nt
	v_add_u32_e32 v34, s12, v192
	v_mul_hi_u32 v35, v34, s13
	v_lshrrev_b32_e32 v35, 10, v35
	v_lshlrev_b32_e32 v34, 4, v34
	v_lshl_add_u32 v69, v35, 13, v34
	s_add_u32 s12, s12, s8
	global_load_dwordx4 v[40:43], v69, s[4:5] nt
	v_add_u32_e32 v34, s12, v192
	v_mul_hi_u32 v35, v34, s13
	v_lshrrev_b32_e32 v35, 10, v35
	v_lshlrev_b32_e32 v34, 4, v34
	v_lshl_add_u32 v70, v35, 13, v34
	s_add_u32 s12, s12, s8
	global_load_dwordx4 v[44:47], v70, s[4:5] nt
	v_add_u32_e32 v34, s12, v192
	v_mul_hi_u32 v35, v34, s13
	v_lshrrev_b32_e32 v35, 10, v35
	v_lshlrev_b32_e32 v34, 4, v34
	v_lshl_add_u32 v71, v35, 13, v34
	s_add_u32 s12, s12, s8
	global_load_dwordx4 v[48:51], v71, s[4:5] nt
	v_add_u32_e32 v34, s12, v192
	v_mul_hi_u32 v35, v34, s13
	v_lshrrev_b32_e32 v35, 10, v35
	v_lshlrev_b32_e32 v34, 4, v34
	v_lshl_add_u32 v72, v35, 13, v34
	s_add_u32 s12, s12, s8
	global_load_dwordx4 v[52:55], v72, s[4:5] nt
	v_add_u32_e32 v34, s12, v192
	v_mul_hi_u32 v35, v34, s13
	v_lshrrev_b32_e32 v35, 10, v35
	v_lshlrev_b32_e32 v34, 4, v34
	v_lshl_add_u32 v73, v35, 13, v34
	s_add_u32 s12, s12, s8
	global_load_dwordx4 v[56:59], v73, s[4:5] nt
	v_add_u32_e32 v34, s12, v192
	v_mul_hi_u32 v35, v34, s13
	v_lshrrev_b32_e32 v35, 10, v35
	v_lshlrev_b32_e32 v34, 4, v34
	v_lshl_add_u32 v74, v35, 13, v34
	s_add_u32 s12, s12, s8
	global_load_dwordx4 v[60:63], v74, s[4:5] nt
	v_add_u32_e32 v34, s12, v192
	v_mul_hi_u32 v35, v34, s13
	v_lshrrev_b32_e32 v35, 10, v35
	v_lshlrev_b32_e32 v34, 4, v34
	v_lshl_add_u32 v75, v35, 13, v34
	s_add_u32 s12, s12, s8
	global_load_dwordx4 v[64:67], v75, s[4:5] nt
	s_waitcnt vmcnt(7)
	global_store_dwordx4 v68, v[36:39], s[6:7] nt
	s_waitcnt vmcnt(7)
	global_store_dwordx4 v69, v[40:43], s[6:7] nt
	s_waitcnt vmcnt(7)
	global_store_dwordx4 v70, v[44:47], s[6:7] nt
	s_waitcnt vmcnt(7)
	global_store_dwordx4 v71, v[48:51], s[6:7] nt
	s_waitcnt vmcnt(7)
	global_store_dwordx4 v72, v[52:55], s[6:7] nt
	s_waitcnt vmcnt(7)
	global_store_dwordx4 v73, v[56:59], s[6:7] nt
	s_waitcnt vmcnt(7)
	global_store_dwordx4 v74, v[60:63], s[6:7] nt
	s_waitcnt vmcnt(7)
	global_store_dwordx4 v75, v[64:67], s[6:7] nt
	s_sub_u32 s10, s10, 8
	s_nop 1
	s_branch .Lp0s_loop_sc
.Lp0s_tail_sc:
	s_cmp_gt_u32 s10, 0
	s_cbranch_scc0 .Lp0s_tl_sc
	v_add_u32_e32 v34, s12, v192
	v_mul_hi_u32 v35, v34, s13
	v_lshrrev_b32_e32 v35, 10, v35
	v_lshlrev_b32_e32 v34, 4, v34
	v_lshl_add_u32 v68, v35, 13, v34
	s_add_u32 s12, s12, s8
	global_load_dwordx4 v[36:39], v68, s[4:5] nt
	s_cmp_gt_u32 s10, 1
	s_cbranch_scc0 .Lp0s_tl_sc
	v_add_u32_e32 v34, s12, v192
	v_mul_hi_u32 v35, v34, s13
	v_lshrrev_b32_e32 v35, 10, v35
	v_lshlrev_b32_e32 v34, 4, v34
	v_lshl_add_u32 v69, v35, 13, v34
	s_add_u32 s12, s12, s8
	global_load_dwordx4 v[40:43], v69, s[4:5] nt
	s_cmp_gt_u32 s10, 2
	s_cbranch_scc0 .Lp0s_tl_sc
	v_add_u32_e32 v34, s12, v192
	v_mul_hi_u32 v35, v34, s13
	v_lshrrev_b32_e32 v35, 10, v35
	v_lshlrev_b32_e32 v34, 4, v34
	v_lshl_add_u32 v70, v35, 13, v34
	s_add_u32 s12, s12, s8
	global_load_dwordx4 v[44:47], v70, s[4:5] nt
	s_cmp_gt_u32 s10, 3
	s_cbranch_scc0 .Lp0s_tl_sc
	v_add_u32_e32 v34, s12, v192
	v_mul_hi_u32 v35, v34, s13
	v_lshrrev_b32_e32 v35, 10, v35
	v_lshlrev_b32_e32 v34, 4, v34
	v_lshl_add_u32 v71, v35, 13, v34
	s_add_u32 s12, s12, s8
	global_load_dwordx4 v[48:51], v71, s[4:5] nt
	s_cmp_gt_u32 s10, 4
	s_cbranch_scc0 .Lp0s_tl_sc
	v_add_u32_e32 v34, s12, v192
	v_mul_hi_u32 v35, v34, s13
	v_lshrrev_b32_e32 v35, 10, v35
	v_lshlrev_b32_e32 v34, 4, v34
	v_lshl_add_u32 v72, v35, 13, v34
	s_add_u32 s12, s12, s8
	global_load_dwordx4 v[52:55], v72, s[4:5] nt
	s_cmp_gt_u32 s10, 5
	s_cbranch_scc0 .Lp0s_tl_sc
	v_add_u32_e32 v34, s12, v192
	v_mul_hi_u32 v35, v34, s13
	v_lshrrev_b32_e32 v35, 10, v35
	v_lshlrev_b32_e32 v34, 4, v34
	v_lshl_add_u32 v73, v35, 13, v34
	s_add_u32 s12, s12, s8
	global_load_dwordx4 v[56:59], v73, s[4:5] nt
	s_cmp_gt_u32 s10, 6
	s_cbranch_scc0 .Lp0s_tl_sc
	v_add_u32_e32 v34, s12, v192
	v_mul_hi_u32 v35, v34, s13
	v_lshrrev_b32_e32 v35, 10, v35
	v_lshlrev_b32_e32 v34, 4, v34
	v_lshl_add_u32 v74, v35, 13, v34
	s_add_u32 s12, s12, s8
	global_load_dwordx4 v[60:63], v74, s[4:5] nt
; __device__ __forceinline__ void p0_prologue(const Args& p, LAS unsigned char* lds, int G, int bid, int tid) {
;     ...
;     for (int i = gt; i < DECB * 1408; i += NT) { const int sb = i / 1408, o = i % 1408; __builtin_nontemporal_store(__builtin_nontemporal_load((const f32x4*)(p.state_pool() + (size_t)sb * 7680 + 2048) + o), (f32x4*)(p.out() + OPS + (size_t)sb * 7680) + o); }
.Lp0s_tl_sc:
	s_waitcnt vmcnt(0)
	s_cmp_gt_u32 s10, 0
	s_cbranch_scc0 .Lp0s_ts_sc
	global_store_dwordx4 v68, v[36:39], s[6:7] nt
	s_cmp_gt_u32 s10, 1
	s_cbranch_scc0 .Lp0s_ts_sc
	global_store_dwordx4 v69, v[40:43], s[6:7] nt
	s_cmp_gt_u32 s10, 2
	s_cbranch_scc0 .Lp0s_ts_sc
	global_store_dwordx4 v70, v[44:47], s[6:7] nt
	s_cmp_gt_u32 s10, 3
	s_cbranch_scc0 .Lp0s_ts_sc
	global_store_dwordx4 v71, v[48:51], s[6:7] nt
	s_cmp_gt_u32 s10, 4
	s_cbranch_scc0 .Lp0s_ts_sc
	global_store_dwordx4 v72, v[52:55], s[6:7] nt
	s_cmp_gt_u32 s10, 5
	s_cbranch_scc0 .Lp0s_ts_sc
	global_store_dwordx4 v73, v[56:59], s[6:7] nt
	s_cmp_gt_u32 s10, 6
	s_cbranch_scc0 .Lp0s_ts_sc
	global_store_dwordx4 v74, v[60:63], s[6:7] nt
.Lp0s_ts_sc:
	s_nop 1
	v_readlane_b32 s4, v242, 31
	v_readlane_b32 s5, v242, 32
	s_nop 3
	s_add_u32 s4, s4, 0x2000
	s_addc_u32 s5, s5, 0
	s_add_u32 s6, s56, 0x5a34000
	s_addc_u32 s7, s57, 0
	s_lshl_b32 s12, s94, 9
	s_lshl_b32 s8, s96, 9
	s_mov_b32 s13, 0x2e8ba2e9
	s_mov_b32 s10, 0
	s_mov_b32 s11, s94
.Lp0s_cnt_sp:
	s_cmp_ge_u32 s11, 0x160
	s_cbranch_scc1 .Lp0s_cntd_sp
	s_add_u32 s10, s10, 1
	s_add_u32 s11, s11, s96
	s_branch .Lp0s_cnt_sp
.Lp0s_cntd_sp:
.Lp0s_loop_sp:
	s_cmp_lt_u32 s10, 8
	s_cbranch_scc1 .Lp0s_tail_sp
	v_add_u32_e32 v34, s12, v192
	v_mul_hi_u32 v35, v34, s13
	v_lshrrev_b32_e32 v35, 8, v35
	v_lshlrev_b32_e32 v34, 4, v34
	v_lshl_add_u32 v68, v35, 13, v34
	s_add_u32 s12, s12, s8
	global_load_dwordx4 v[36:39], v68, s[4:5] nt
	v_add_u32_e32 v34, s12, v192
	v_mul_hi_u32 v35, v34, s13
	v_lshrrev_b32_e32 v35, 8, v35
	v_lshlrev_b32_e32 v34, 4, v34
	v_lshl_add_u32 v69, v35, 13, v34
	s_add_u32 s12, s12, s8
	global_load_dwordx4 v[40:43], v69, s[4:5] nt
	v_add_u32_e32 v34, s12, v192
	v_mul_hi_u32 v35, v34, s13
	v_lshrrev_b32_e32 v35, 8, v35
	v_lshlrev_b32_e32 v34, 4, v34
	v_lshl_add_u32 v70, v35, 13, v34
	s_add_u32 s12, s12, s8
	global_load_dwordx4 v[44:47], v70, s[4:5] nt
	v_add_u32_e32 v34, s12, v192
	v_mul_hi_u32 v35, v34, s13
	v_lshrrev_b32_e32 v35, 8, v35
	v_lshlrev_b32_e32 v34, 4, v34
	v_lshl_add_u32 v71, v35, 13, v34
	s_add_u32 s12, s12, s8
	global_load_dwordx4 v[48:51], v71, s[4:5] nt
	v_add_u32_e32 v34, s12, v192
	v_mul_hi_u32 v35, v34, s13
	v_lshrrev_b32_e32 v35, 8, v35
	v_lshlrev_b32_e32 v34, 4, v34
	v_lshl_add_u32 v72, v35, 13, v34
	s_add_u32 s12, s12, s8
	global_load_dwordx4 v[52:55], v72, s[4:5] nt
	v_add_u32_e32 v34, s12, v192
	v_mul_hi_u32 v35, v34, s13
	v_lshrrev_b32_e32 v35, 8, v35
	v_lshlrev_b32_e32 v34, 4, v34
	v_lshl_add_u32 v73, v35, 13, v34
	s_add_u32 s12, s12, s8
	global_load_dwordx4 v[56:59], v73, s[4:5] nt
	v_add_u32_e32 v34, s12, v192
	v_mul_hi_u32 v35, v34, s13
	v_lshrrev_b32_e32 v35, 8, v35
	v_lshlrev_b32_e32 v34, 4, v34
	v_lshl_add_u32 v74, v35, 13, v34
	s_add_u32 s12, s12, s8
	global_load_dwordx4 v[60:63], v74, s[4:5] nt
	v_add_u32_e32 v34, s12, v192
	v_mul_hi_u32 v35, v34, s13
	v_lshrrev_b32_e32 v35, 8, v35
	v_lshlrev_b32_e32 v34, 4, v34
	v_lshl_add_u32 v75, v35, 13, v34
	s_add_u32 s12, s12, s8
	global_load_dwordx4 v[64:67], v75, s[4:5] nt
	s_waitcnt vmcnt(7)
	global_store_dwordx4 v68, v[36:39], s[6:7] nt
	s_waitcnt vmcnt(7)
	global_store_dwordx4 v69, v[40:43], s[6:7] nt
	s_waitcnt vmcnt(7)
	global_store_dwordx4 v70, v[44:47], s[6:7] nt
	s_waitcnt vmcnt(7)
	global_store_dwordx4 v71, v[48:51], s[6:7] nt
	s_waitcnt vmcnt(7)
	global_store_dwordx4 v72, v[52:55], s[6:7] nt
	s_waitcnt vmcnt(7)
	global_store_dwordx4 v73, v[56:59], s[6:7] nt
	s_waitcnt vmcnt(7)
	global_store_dwordx4 v74, v[60:63], s[6:7] nt
	s_waitcnt vmcnt(7)
	global_store_dwordx4 v75, v[64:67], s[6:7] nt
	s_sub_u32 s10, s10, 8
	s_nop 1
	s_branch .Lp0s_loop_sp
.Lp0s_tail_sp:
	s_cmp_gt_u32 s10, 0
	s_cbranch_scc0 .Lp0s_tl_sp
	v_add_u32_e32 v34, s12, v192
	v_mul_hi_u32 v35, v34, s13
	v_lshrrev_b32_e32 v35, 8, v35
	v_lshlrev_b32_e32 v34, 4, v34
	v_lshl_add_u32 v68, v35, 13, v34
	s_add_u32 s12, s12, s8
	global_load_dwordx4 v[36:39], v68, s[4:5] nt
	s_cmp_gt_u32 s10, 1
	s_cbranch_scc0 .Lp0s_tl_sp
	v_add_u32_e32 v34, s12, v192
	v_mul_hi_u32 v35, v34, s13
	v_lshrrev_b32_e32 v35, 8, v35
	v_lshlrev_b32_e32 v34, 4, v34
	v_lshl_add_u32 v69, v35, 13, v34
	s_add_u32 s12, s12, s8
	global_load_dwordx4 v[40:43], v69, s[4:5] nt
	s_cmp_gt_u32 s10, 2
	s_cbranch_scc0 .Lp0s_tl_sp
	v_add_u32_e32 v34, s12, v192
	v_mul_hi_u32 v35, v34, s13
	v_lshrrev_b32_e32 v35, 8, v35
	v_lshlrev_b32_e32 v34, 4, v34
	v_lshl_add_u32 v70, v35, 13, v34
	s_add_u32 s12, s12, s8
	global_load_dwordx4 v[44:47], v70, s[4:5] nt
	s_cmp_gt_u32 s10, 3
	s_cbranch_scc0 .Lp0s_tl_sp
	v_add_u32_e32 v34, s12, v192
	v_mul_hi_u32 v35, v34, s13
	v_lshrrev_b32_e32 v35, 8, v35
	v_lshlrev_b32_e32 v34, 4, v34
	v_lshl_add_u32 v71, v35, 13, v34
	s_add_u32 s12, s12, s8
	global_load_dwordx4 v[48:51], v71, s[4:5] nt
	s_cmp_gt_u32 s10, 4
	s_cbranch_scc0 .Lp0s_tl_sp
	v_add_u32_e32 v34, s12, v192
	v_mul_hi_u32 v35, v34, s13
	v_lshrrev_b32_e32 v35, 8, v35
	v_lshlrev_b32_e32 v34, 4, v34
	v_lshl_add_u32 v72, v35, 13, v34
	s_add_u32 s12, s12, s8
	global_load_dwordx4 v[52:55], v72, s[4:5] nt
	s_cmp_gt_u32 s10, 5
	s_cbranch_scc0 .Lp0s_tl_sp
	v_add_u32_e32 v34, s12, v192
	v_mul_hi_u32 v35, v34, s13
	v_lshrrev_b32_e32 v35, 8, v35
	v_lshlrev_b32_e32 v34, 4, v34
	v_lshl_add_u32 v73, v35, 13, v34
	s_add_u32 s12, s12, s8
	global_load_dwordx4 v[56:59], v73, s[4:5] nt
	s_cmp_gt_u32 s10, 6
	s_cbranch_scc0 .Lp0s_tl_sp
	v_add_u32_e32 v34, s12, v192
	v_mul_hi_u32 v35, v34, s13
	v_lshrrev_b32_e32 v35, 8, v35
	v_lshlrev_b32_e32 v34, 4, v34
	v_lshl_add_u32 v74, v35, 13, v34
	s_add_u32 s12, s12, s8
	global_load_dwordx4 v[60:63], v74, s[4:5] nt

; __device__ __forceinline__ unsigned xb_ld(unsigned* p)              { return __hip_atomic_load(p, __ATOMIC_RELAXED, __HIP_MEMORY_SCOPE_AGENT); }
; __device__ __forceinline__ void xcd_barrier_complete(unsigned* bar, unsigned x, unsigned& nloc, unsigned& nx) {
;     const unsigned G = gridDim.x * gridDim.y * gridDim.z;
;     unsigned sum, cnt, mine, sp = 0u;
;     for (;;) {
;         sum = 0u; cnt = 0u; mine = 0u;
; #pragma unroll
;         for (unsigned j = 0; j < 16; ++j) { const unsigned c = xb_ld(&bar[XB_XCNT(j)]); sum += c; cnt += (c > 0u) ? 1u : 0u; mine = (j == x) ? c : mine; }
; __device__ __forceinline__ void xcd_barrier(const XcdBarrier& b) {
;     asm volatile("s_waitcnt vmcnt(0)" ::: "memory");
;     __syncthreads();
;     if (threadIdx.x == 0) {
;         unsigned* bar = b.bar;
;         __builtin_amdgcn_s_waitcnt(0);
;         unsigned nloc = b.st[0], nx = b.st[1];
;         if (nloc == 0u) { xcd_barrier_complete(bar, b.x, nloc, nx); b.st[0] = nloc; b.st[1] = nx; }
.Lp0s_ts_sp:
	s_nop 1
	s_cmp_lt_i32 s89, 2
	s_cbranch_scc1 .LBB0_158
	s_waitcnt vmcnt(0)
	s_waitcnt lgkmcnt(0)
	s_barrier
	s_mov_b64 s[0:1], exec
	v_readlane_b32 s2, v242, 1
	v_readlane_b32 s3, v242, 2
	s_and_b64 s[2:3], s[0:1], s[2:3]
	s_mov_b64 exec, s[2:3]
	s_cbranch_execz .LBB0_157
	s_add_i32 s2, 0, 0x21fc0
	v_mov_b32_e32 v0, s2
	s_waitcnt vmcnt(0) expcnt(0) lgkmcnt(0)
	ds_read_b32 v2, v0
	s_add_i32 s2, 0, 0x21fc4
	v_mov_b32_e32 v0, s2
	ds_read_b32 v0, v0
	s_waitcnt lgkmcnt(1)
	v_cmp_ne_u32_e32 vcc, 0, v2
	s_cbranch_vccnz .LBB0_121
	v_readlane_b32 s2, v242, 0
	s_mul_i32 s33, s97, s2
	s_add_u32 s2, s58, 0x50200
	s_addc_u32 s3, s59, 0
	s_add_u32 s4, s58, 0x50400
	s_addc_u32 s5, s59, 0
	s_add_u32 s6, s58, 0x50500
	s_addc_u32 s7, s59, 0
	s_add_u32 s8, s58, 0x50600
	s_addc_u32 s9, s59, 0
	s_add_u32 s10, s58, 0x50700
	s_addc_u32 s11, s59, 0
	s_add_u32 s12, s58, 0x50800
	s_addc_u32 s13, s59, 0
	s_add_u32 s14, s58, 0x50900
	s_addc_u32 s15, s59, 0
	s_add_u32 s16, s58, 0x50a00
	s_addc_u32 s17, s59, 0
	s_add_u32 s18, s58, 0x50b00
	s_addc_u32 s19, s59, 0
	s_add_u32 s20, s58, 0x50c00
	s_addc_u32 s21, s59, 0
	s_add_u32 s22, s58, 0x50d00
	s_addc_u32 s23, s59, 0
	s_add_u32 s24, s58, 0x50e00
	s_addc_u32 s25, s59, 0
	s_add_u32 s26, s58, 0x50f00
	s_addc_u32 s27, s59, 0
	s_add_u32 s28, s58, 0x51000
	s_addc_u32 s29, s59, 0
	s_add_u32 s30, s58, 0x51100
	s_addc_u32 s31, s59, 0
	s_add_u32 s34, s58, 0x51200
	s_addc_u32 s35, s59, 0
	s_add_u32 s36, s58, 0x51300
	s_mul_i32 s33, s33, s96
	s_addc_u32 s37, s59, 0
	s_mov_b32 s40, 1
	v_mov_b32_e32 v16, 0
	s_branch .LBB0_109
